# no entry grid.sync + 4-byte pad so downstream code keeps the baseline 8-byte placement phase
# speedup vs baseline: 1.0254x; 1.0055x over previous
; __global__ void __launch_bounds__(512, 2) mega_fwd(Args args) {
;     ...
;     XcdBarrier xbar = xcd_barrier_post((unsigned*)(args.ws), bst);
;     grid.sync();
;     bf16_t* XB = (bf16_t*)(c.ws + WS_XB);
;     for (int ph = args.ph_lo; ph < args.ph_hi; ++ph) {
;         const int l = ph / PH_PER_LAYER, k = ph % PH_PER_LAYER;
;         { int t_ = threadIdx.x; asm volatile("" : "+v"(t_)); c.tid = t_; c.lane = t_ & 63; c.wave = __builtin_amdgcn_readfirstlane(t_ >> 6);
;           int z_ = 0; asm volatile("" : "+s"(z_)); c.zero = z_;
;           int bx = blockIdx.x; asm volatile("" : "+s"(bx)); c.vcu = (c.G % 8 == 0) ? (bx % 8) * (c.G / 8) + bx / 8 : bx; }
.LBB0_15:
	s_nop 0
	s_or_b64 exec, exec, s[4:5]
	v_readlane_b32 s4, v253, 0
	v_readlane_b32 s5, v253, 1
	s_load_dwordx2 s[4:5], s[4:5], 0xb8
	s_barrier
	s_waitcnt lgkmcnt(0)
	v_writelane_b32 v253, s4, 4
	s_cmp_ge_i32 s4, s5
	s_nop 0
	v_writelane_b32 v253, s5, 5
	s_cbranch_scc1 .LBB0_572
	v_readlane_b32 s16, v253, 0
	v_readlane_b32 s17, v253, 1
	s_load_dwordx4 s[12:15], s[16:17], 0xa8
	s_mov_b32 s84, 0xffff0000
	v_mbcnt_lo_u32_b32 v0, -1, 0
	v_mov_b32_e32 v97, 0
	v_mov_b32_e32 v213, 0x260
	s_waitcnt lgkmcnt(0)
	s_add_u32 s82, s14, 0x1a000000
	s_addc_u32 s83, s15, 0
	s_and_b32 s1, s58, 7
	s_cmp_eq_u32 s1, 0
	s_cselect_b64 s[4:5], -1, 0
	v_writelane_b32 v253, s4, 6
	s_ashr_i32 s1, s58, 3
	v_mov_b32_e32 v214, 0x2000
	v_writelane_b32 v253, s5, 7
	s_add_u32 s4, s14, 0x1400000
	s_addc_u32 s5, s15, 0
	s_add_u32 s33, s14, 0xe000000
	s_addc_u32 s37, s15, 0
	s_add_u32 s89, s14, 0x4000000
	v_writelane_b32 v253, s1, 8
	s_addc_u32 s3, s15, 0
	v_writelane_b32 v253, s4, 9
	s_cmpk_lt_i32 s2, 0x200
	v_mov_b32_e32 v215, 0x3c0881c4
	v_writelane_b32 v253, s5, 10
	s_cselect_b64 s[4:5], -1, 0
	s_ashr_i32 s78, s2, 31
	v_writelane_b32 v253, s4, 11
	s_lshr_b32 s1, s78, 29
	s_ashr_i32 s79, s58, 31
	v_writelane_b32 v253, s5, 12
	s_add_i32 s4, s2, s1
	s_ashr_i32 s1, s4, 3
	s_and_b32 s4, s4, -8
	s_sub_i32 s6, s2, s4
	s_lshl_b32 s7, s6, 6
	s_add_u32 s90, s14, 0x2000000
	s_addc_u32 s91, s15, 0
	s_add_u32 s4, s14, 0x1800000
	s_addc_u32 s5, s15, 0
	v_writelane_b32 v253, s4, 13
	s_cmpk_lt_i32 s2, 0x80
	v_mov_b32_e32 v216, 0xbab64f3b
	v_writelane_b32 v253, s5, 14
	s_cselect_b64 s[4:5], -1, 0
	v_writelane_b32 v253, s4, 15
	s_lshl_b32 s8, s6, 4
	v_mov_b32_e32 v217, 0xda24260
	v_writelane_b32 v253, s5, 16
	s_add_u32 s4, s14, 0x1800080
	s_addc_u32 s5, s15, 0
	v_writelane_b32 v253, s4, 17
	v_mov_b32_e32 v218, 0x3ecc95a3
	v_mov_b32_e32 v219, 0x3727c5ac
	v_writelane_b32 v253, s5, 18
	s_add_u32 s4, s14, 0x3800
	v_writelane_b32 v253, s4, 19
	s_addc_u32 s4, s15, 0
	v_writelane_b32 v253, s4, 20
	s_add_u32 s4, s14, 0x200000
	s_addc_u32 s5, s15, 0
	s_lshl_b32 s26, s58, 3
	s_add_u32 s10, s14, 0xc000000
	s_addc_u32 s11, s15, 0
	v_writelane_b32 v253, s10, 21
	v_mov_b32_e32 v220, 0x23fc0
	v_mov_b32_e32 v221, 0x23fc4
	v_writelane_b32 v253, s11, 22
	s_add_u32 s10, s14, 0x300000
	s_addc_u32 s11, s15, 0
	s_add_u32 s27, s14, 0x6000000
	s_addc_u32 s28, s15, 0
	s_add_u32 s29, s14, 0x8000000
	v_writelane_b32 v253, s10, 23
	s_addc_u32 s30, s15, 0
	v_mov_b32_e32 v222, 1
	v_writelane_b32 v253, s11, 24
	s_add_u32 s10, s14, 0xa000000
	s_addc_u32 s11, s15, 0
	s_add_u32 s9, s14, 0x100000
	v_writelane_b32 v253, s9, 25
	s_addc_u32 s9, s15, 0
	s_add_u32 s12, s14, 0x800000
	v_writelane_b32 v253, s9, 26
	s_addc_u32 s13, s15, 0
	v_writelane_b32 v253, s12, 27
	s_cmpk_lt_i32 s2, 0xc00
	v_mov_b64_e32 v[194:195], 0x200
	v_writelane_b32 v253, s13, 28
	s_cselect_b64 s[12:13], -1, 0
	v_writelane_b32 v253, s12, 29
	v_mov_b64_e32 v[196:197], 0x1ff
	v_mov_b32_e32 v223, 0x7f800000
	v_writelane_b32 v253, s13, 30
	s_add_u32 s12, s14, 0x1600000
	s_addc_u32 s13, s15, 0
	v_writelane_b32 v253, s12, 31
	v_not_b32_e32 v224, 63
	v_not_b32_e32 v225, 31
	v_writelane_b32 v253, s13, 32
	s_add_u32 s12, s14, 0x1400600
	s_addc_u32 s13, s15, 0
	v_writelane_b32 v253, s12, 33
	v_mov_b32_e32 v226, 0x7fc00000
	v_mov_b32_e32 v227, 0xff800000
	v_writelane_b32 v253, s13, 34
	s_add_u32 s12, s14, 0x1400200
	s_addc_u32 s13, s15, 0
	v_writelane_b32 v253, s12, 35
	s_add_u32 s9, s14, 0x400000
	v_mbcnt_hi_u32_b32 v228, -1, v0
	v_writelane_b32 v253, s13, 36
	v_writelane_b32 v253, s9, 37
	s_addc_u32 s9, s15, 0
	s_add_u32 s12, s14, 0x200
	v_writelane_b32 v253, s9, 38
	s_addc_u32 s13, s15, 0
	v_writelane_b32 v253, s12, 39
	v_mov_b64_e32 v[198:199], 0xbff
	s_mov_b32 s87, 0xf800000
	v_writelane_b32 v253, s13, 40
	s_add_u32 s12, s14, 0x1000
	s_addc_u32 s13, s15, 0
	v_writelane_b32 v253, s12, 41
	s_mov_b32 s93, 0xc3160000
	s_mov_b32 s95, 0x41c00000
	v_writelane_b32 v253, s13, 42
	s_add_u32 s12, s14, 0x1100
	s_addc_u32 s13, s15, 0
	v_writelane_b32 v253, s12, 43
	s_mov_b32 s35, 0
	s_mov_b64 s[96:97], 0x4000
	v_writelane_b32 v253, s13, 44
	s_add_u32 s12, s14, 0x1200
	s_addc_u32 s13, s15, 0
	v_writelane_b32 v253, s12, 45
	s_mov_b64 s[18:19], 0x10000
	s_mov_b64 s[56:57], 0x20000
	v_writelane_b32 v253, s13, 46
	s_add_u32 s12, s14, 0x1300
	s_addc_u32 s13, s15, 0
	v_writelane_b32 v253, s12, 47
	s_cmp_eq_u32 s0, 15
	s_mov_b32 s85, -1
	v_writelane_b32 v253, s13, 48
	s_cselect_b64 s[12:13], -1, 0
	v_writelane_b32 v253, s12, 49
	s_cmp_eq_u32 s0, 14
	s_mov_b32 s88, 0x3fd744fd
	v_writelane_b32 v253, s13, 50
	s_cselect_b64 s[12:13], -1, 0
	v_writelane_b32 v253, s12, 51
	s_cmp_eq_u32 s0, 13
; __device__ __forceinline__ unsigned xb_ld(unsigned* p)              { return __hip_atomic_load(p, __ATOMIC_RELAXED, __HIP_MEMORY_SCOPE_AGENT); }
;     __host__ __device__ bool next(int i, Unit& u) const {
;         const long L = (long)i * G + c; if (L >= nwg) return false;
;         int wgid = (int)L; { const int q = nwg / NXCD, r = nwg % NXCD, xcd = wgid % NXCD, off = wgid / NXCD; wgid = (xcd < r ? xcd * (q + 1) : r * (q + 1) + (xcd - r) * q) + off; }
;         const int nig = WGM * nN, gid = wgid / nig, fm = gid * WGM, gsz = (nM - fm) < WGM ? (nM - fm) : WGM;
;         u.pm = fm + ((wgid % nig) % gsz); u.pn = (wgid % nig) / gsz; return true;
;     }
; __device__ __forceinline__ void xcd_barrier_complete(unsigned* bar, unsigned x, unsigned& nloc, unsigned& nx) {
;     const unsigned G = gridDim.x * gridDim.y * gridDim.z;
;     unsigned sum, cnt, mine, sp = 0u;
;     for (;;) {
;         sum = 0u; cnt = 0u; mine = 0u;
; #pragma unroll
;         for (unsigned j = 0; j < 16; ++j) { const unsigned c = xb_ld(&bar[XB_XCNT(j)]); sum += c; cnt += (c > 0u) ? 1u : 0u; mine = (j == x) ? c : mine; }
;         if (sum == G) break;
;         __builtin_amdgcn_s_sleep(1);
;         if ((++sp & 255u) == 0u) { if (xb_ld(&bar[XB_TMO])) break; if (sp > XB_SPIN_CAP) { atomicAdd(&bar[XB_TMO], 1u); break; } }
;     }
;     nloc = mine > 0u ? mine : 1u; nx = cnt > 0u ? cnt : 1u;
	s_nop 0
	v_writelane_b32 v253, s13, 52
	s_cselect_b64 s[12:13], -1, 0
	v_writelane_b32 v253, s12, 53
	s_cmp_eq_u32 s0, 12
	s_nop 0
	v_writelane_b32 v253, s13, 54
	s_cselect_b64 s[12:13], -1, 0
	v_writelane_b32 v253, s12, 55
	s_cmp_eq_u32 s0, 11
	s_nop 0
	v_writelane_b32 v253, s13, 56
	s_cselect_b64 s[12:13], -1, 0
	v_writelane_b32 v253, s12, 57
	s_cmp_eq_u32 s0, 10
	s_nop 0
	v_writelane_b32 v253, s13, 58
	s_cselect_b64 s[12:13], -1, 0
	v_writelane_b32 v253, s12, 59
	s_cmp_eq_u32 s0, 9
	s_nop 0
	v_writelane_b32 v253, s13, 60
	s_cselect_b64 s[12:13], -1, 0
	v_writelane_b32 v253, s12, 61
	s_cmp_eq_u32 s0, 8
	s_nop 0
	v_writelane_b32 v253, s13, 62
	s_cselect_b64 s[12:13], -1, 0
	v_writelane_b32 v253, s12, 63
	s_cmp_eq_u32 s0, 7
	s_nop 0
	v_writelane_b32 v252, s13, 0
	s_cselect_b64 s[12:13], -1, 0
	v_writelane_b32 v252, s12, 1
	s_cmp_eq_u32 s0, 6
	s_nop 0
	v_writelane_b32 v252, s13, 2
	s_cselect_b64 s[12:13], -1, 0
	v_writelane_b32 v252, s12, 3
	s_cmp_eq_u32 s0, 5
	s_nop 0
	v_writelane_b32 v252, s13, 4
	s_cselect_b64 s[12:13], -1, 0
	v_writelane_b32 v252, s12, 5
	s_cmp_eq_u32 s0, 4
	s_nop 0
	v_writelane_b32 v252, s13, 6
	s_cselect_b64 s[12:13], -1, 0
	v_writelane_b32 v252, s12, 7
	s_cmp_eq_u32 s0, 3
	s_nop 0
	v_writelane_b32 v252, s13, 8
	s_cselect_b64 s[12:13], -1, 0
	v_writelane_b32 v252, s12, 9
	s_cmp_eq_u32 s0, 2
	s_nop 0
	v_writelane_b32 v252, s13, 10
	s_cselect_b64 s[12:13], -1, 0
	v_writelane_b32 v252, s12, 11
	s_cmp_eq_u32 s0, 1
	s_nop 0
	v_writelane_b32 v252, s13, 12
	s_cselect_b64 s[12:13], -1, 0
	v_writelane_b32 v252, s12, 13
	s_cmp_eq_u32 s0, 0
	s_nop 0
	v_writelane_b32 v252, s13, 14
	s_cselect_b64 s[12:13], -1, 0
	s_lshl_b32 s0, s0, 8
	s_add_u32 s0, s14, s0
	v_writelane_b32 v252, s12, 15
	s_addc_u32 s9, s15, 0
	s_nop 0
	v_writelane_b32 v252, s13, 16
	s_add_u32 s12, s0, 0x1400
	s_addc_u32 s13, s9, 0
	v_writelane_b32 v252, s12, 17
	s_nop 1
	v_writelane_b32 v252, s13, 18
	s_add_u32 s12, s0, 0x2400
	s_addc_u32 s13, s9, 0
	v_writelane_b32 v252, s12, 19
	s_mul_i32 s0, s6, 0x41
	s_nop 0
	v_writelane_b32 v252, s13, 20
	s_add_u32 s12, s14, 0x3400
	s_addc_u32 s13, s15, 0
	v_writelane_b32 v252, s12, 21
	s_nop 1
	v_writelane_b32 v252, s13, 22
	s_add_u32 s12, s14, 0x3500
	s_addc_u32 s13, s15, 0
	s_cmp_lt_i32 s6, 0
	s_cselect_b32 s0, s0, s7
	s_mul_i32 s7, s6, 17
	s_cselect_b32 s7, s7, s8
	s_movk_i32 s8, 0x181
	s_cselect_b32 s8, s8, 0x180
	s_add_i32 s0, s0, s1
	s_ashr_i32 s9, s0, 31
	s_lshr_b32 s9, s9, 28
	v_writelane_b32 v252, s12, 23
	s_add_i32 s9, s0, s9
	s_nop 0
	v_writelane_b32 v252, s13, 24
	s_and_b32 s12, s9, 0xfff0
	s_sub_i32 s0, s0, s12
	s_bfe_i32 s12, s0, 0x80000
	s_bfe_u32 s12, s12, 0x2000d
	s_add_i32 s12, s0, s12
	s_and_b32 s13, s12, 0xfc
	s_sub_i32 s0, s0, s13
	s_ashr_i32 s9, s9, 4
	s_lshl_b32 s9, s9, 2
	s_sext_i32_i8 s0, s0
	s_add_i32 s9, s9, s0
	s_mul_i32 s0, s6, s8
	s_add_i32 s0, s0, s1
	s_add_i32 s8, s7, s1
	s_mul_hi_i32 s1, s0, 0x2aaaaaab
	s_lshr_b32 s6, s1, 31
	s_ashr_i32 s1, s1, 4
	s_add_i32 s1, s1, s6
	s_mul_i32 s6, s1, 0x60
	s_sub_i32 s0, s0, s6
	s_bfe_i32 s6, s0, 0x80000
	s_bfe_u32 s6, s6, 0x2000d
	s_add_i32 s6, s0, s6
	s_and_b32 s7, s6, 0xfc
	s_sub_i32 s0, s0, s7
	s_lshl_b32 s1, s1, 2
	s_sext_i32_i8 s0, s0
	s_add_i32 s13, s1, s0
	s_load_dword s0, s[16:17], 0xc8
	s_waitcnt lgkmcnt(0)
	s_mul_i32 s0, s59, s0
	s_mul_i32 s0, s0, s58
	v_writelane_b32 v252, s0, 25
	s_bfe_i32 s0, s12, 0x80000
	s_sext_i32_i16 s0, s0
	s_ashr_i32 s1, s0, 2
	s_lshr_b32 s0, s0, 2
	v_writelane_b32 v252, s1, 26
	s_bfe_i64 s[0:1], s[0:1], 0x100000
	v_writelane_b32 v252, s0, 27
	s_mov_b32 s59, 0xffff0000
	s_nop 0
	v_writelane_b32 v252, s1, 28
	s_bfe_i32 s0, s6, 0x80000
	s_sext_i32_i16 s0, s0
	s_lshr_b32 s0, s0, 2
	s_sext_i32_i16 s1, s0
	v_writelane_b32 v252, s9, 29
	s_ashr_i32 s9, s9, 31
	s_lshl_b32 s6, s1, 8
	v_writelane_b32 v252, s9, 30
	s_ashr_i32 s7, s6, 31
	v_writelane_b32 v252, s8, 31
	s_ashr_i32 s8, s8, 31
	v_writelane_b32 v252, s8, 32
	s_cmp_lt_i32 s1, 8
	v_writelane_b32 v252, s1, 33
	s_cselect_b32 s1, 0, 8
	s_bfe_i64 s[8:9], s[0:1], 0x100000
	v_writelane_b32 v252, s8, 34
	s_ashr_i32 s0, s13, 31
	s_nop 0
	v_writelane_b32 v252, s9, 35
	v_writelane_b32 v252, s13, 36
	s_add_u32 s8, s14, 0xc008000
	v_writelane_b32 v252, s0, 37
	s_addc_u32 s9, s15, 0
	v_writelane_b32 v252, s8, 38
	s_lshl_b64 s[6:7], s[6:7], 2
	s_lshl_b32 s0, s1, 2
	v_writelane_b32 v252, s9, 39
	v_writelane_b32 v252, s6, 40
	s_mov_b32 s1, 0x2002000
	s_mov_b64 s[8:9], 0x80
	v_writelane_b32 v252, s7, 41
	v_writelane_b32 v252, s0, 42
	s_lshl_b32 s0, s58, 7
	v_writelane_b32 v252, s0, 43
	s_brev_b32 s7, 64
	s_mov_b64 s[14:15], 0x30000
	v_writelane_b32 v252, s78, 44
	v_writelane_b32 v252, s79, 45
	s_branch .LBB0_20
